# idx top-k selection rewritten by hand: float FMA+clamp indicator counting in VGPRs instead of v_cmp/v_addc through SGPRs; scalar adds
# speedup vs baseline: 1.0287x; 1.0287x over previous
.LBB0_820:
	s_waitcnt vmcnt(0) lgkmcnt(0)
	s_barrier
	s_lshl_b32 s26, s5, 1
	s_mov_b32 s36, 0xec800000
	s_mov_b32 s37, 0x6c800000
	v_mov_b32_e32 v149, 0xd1800000
	v_lshlrev_b32_e32 v152, 2, v197
	s_mov_b32 s4, 0
.Lsel_row:
	s_or_b32 s27, s26, s4
	s_mul_i32 s0, s27, 0x2010
	v_add_u32_e32 v145, s0, v152
	s_add_i32 s27, s27, s33
	ds_read2st64_b32 v[102:103], v145 offset0:0 offset1:1
	ds_read2st64_b32 v[104:105], v145 offset0:2 offset1:3
	ds_read2st64_b32 v[106:107], v145 offset0:4 offset1:5
	ds_read2st64_b32 v[108:109], v145 offset0:6 offset1:7
	ds_read2st64_b32 v[110:111], v145 offset0:8 offset1:9
	ds_read2st64_b32 v[112:113], v145 offset0:10 offset1:11
	ds_read2st64_b32 v[114:115], v145 offset0:12 offset1:13
	ds_read2st64_b32 v[116:117], v145 offset0:14 offset1:15
	ds_read2st64_b32 v[118:119], v145 offset0:16 offset1:17
	ds_read2st64_b32 v[120:121], v145 offset0:18 offset1:19
	ds_read2st64_b32 v[122:123], v145 offset0:20 offset1:21
	ds_read2st64_b32 v[124:125], v145 offset0:22 offset1:23
	ds_read2st64_b32 v[126:127], v145 offset0:24 offset1:25
	ds_read2st64_b32 v[128:129], v145 offset0:26 offset1:27
	ds_read2st64_b32 v[130:131], v145 offset0:28 offset1:29
	ds_read2st64_b32 v[132:133], v145 offset0:30 offset1:31
	v_sub_u32_e32 v143, s27, v197
	v_ashrrev_i32_e32 v143, 6, v143
	v_lshlrev_b32_e64 v151, v143, -2
	v_not_b32_e32 v151, v151
	v_ashrrev_i32_e32 v144, 31, v143
	v_bfi_b32 v151, v144, 0, v151
	s_waitcnt lgkmcnt(0)
	v_bfe_i32 v134, v151, 0, 1
	v_bfi_b32 v102, v134, v102, v149
	v_bfe_i32 v135, v151, 1, 1
	v_bfi_b32 v103, v135, v103, v149
	v_bfe_i32 v134, v151, 2, 1
	v_bfi_b32 v104, v134, v104, v149
	v_bfe_i32 v135, v151, 3, 1
	v_bfi_b32 v105, v135, v105, v149
	v_bfe_i32 v134, v151, 4, 1
	v_bfi_b32 v106, v134, v106, v149
	v_bfe_i32 v135, v151, 5, 1
	v_bfi_b32 v107, v135, v107, v149
	v_bfe_i32 v134, v151, 6, 1
	v_bfi_b32 v108, v134, v108, v149
	v_bfe_i32 v135, v151, 7, 1
	v_bfi_b32 v109, v135, v109, v149
	v_bfe_i32 v134, v151, 8, 1
	v_bfi_b32 v110, v134, v110, v149
	v_bfe_i32 v135, v151, 9, 1
	v_bfi_b32 v111, v135, v111, v149
	v_bfe_i32 v134, v151, 10, 1
	v_bfi_b32 v112, v134, v112, v149
	v_bfe_i32 v135, v151, 11, 1
	v_bfi_b32 v113, v135, v113, v149
	v_bfe_i32 v134, v151, 12, 1
	v_bfi_b32 v114, v134, v114, v149
	v_bfe_i32 v135, v151, 13, 1
	v_bfi_b32 v115, v135, v115, v149
	v_bfe_i32 v134, v151, 14, 1
	v_bfi_b32 v116, v134, v116, v149
	v_bfe_i32 v135, v151, 15, 1
	v_bfi_b32 v117, v135, v117, v149
	v_bfe_i32 v134, v151, 16, 1
	v_bfi_b32 v118, v134, v118, v149
	v_bfe_i32 v135, v151, 17, 1
	v_bfi_b32 v119, v135, v119, v149
	v_bfe_i32 v134, v151, 18, 1
	v_bfi_b32 v120, v134, v120, v149
	v_bfe_i32 v135, v151, 19, 1
	v_bfi_b32 v121, v135, v121, v149
	v_bfe_i32 v134, v151, 20, 1
	v_bfi_b32 v122, v134, v122, v149
	v_bfe_i32 v135, v151, 21, 1
	v_bfi_b32 v123, v135, v123, v149
	v_bfe_i32 v134, v151, 22, 1
	v_bfi_b32 v124, v134, v124, v149
	v_bfe_i32 v135, v151, 23, 1
	v_bfi_b32 v125, v135, v125, v149
	v_bfe_i32 v134, v151, 24, 1
	v_bfi_b32 v126, v134, v126, v149
	v_bfe_i32 v135, v151, 25, 1
	v_bfi_b32 v127, v135, v127, v149
	v_bfe_i32 v134, v151, 26, 1
	v_bfi_b32 v128, v134, v128, v149
	v_bfe_i32 v135, v151, 27, 1
	v_bfi_b32 v129, v135, v129, v149
	v_bfe_i32 v134, v151, 28, 1
	v_bfi_b32 v130, v134, v130, v149
	v_bfe_i32 v135, v151, 29, 1
	v_bfi_b32 v131, v135, v131, v149
	v_bfe_i32 v134, v151, 30, 1
	v_bfi_b32 v132, v134, v132, v149
	v_bfe_i32 v135, v151, 31, 1
	v_bfi_b32 v133, v135, v133, v149
	s_cmpk_gt_i32 s27, 0xff
	s_cbranch_scc1 .Lsel_search
	s_mov_b32 s0, 0xd1400000
	s_branch .Lsel_mask
.Lsel_search:
	s_mov_b32 s29, 0x00800000
	s_mov_b32 s30, 0xff800000
	s_mov_b32 s31, -1
.Lsel_bis:
	s_sub_u32 s0, s30, s29
	s_cmp_lt_u32 s0, 2
	s_cbranch_scc1 .Lsel_bis_done
	s_lshr_b32 s0, s0, 1
	s_add_u32 s6, s29, s0
	s_mov_b32 s7, s6
	s_sub_u32 s1, s7, 0x60800000
	s_cmp_lt_u32 s1, 0x3f000000
	s_cbranch_scc0 .Lsel_nosnap1
	s_mov_b32 s1, 0x9f800000
	s_cmp_lt_u32 s7, 0x80000000
	s_cselect_b32 s1, 0x80000000, s1
	s_cmp_eq_u32 s7, 0x80000000
	s_cselect_b32 s7, s7, s1
.Lsel_nosnap1:
	s_xor_b32 s1, s7, 0x80000000
	s_not_b32 s0, s7
	s_bitcmp1_b32 s7, 31
	s_cselect_b32 s0, s1, s0
	v_mov_b32_e32 v142, s0
	v_mul_f32_e32 v142, s37, v142
	v_fma_f32 v138, v102, s36, v142 clamp
	v_fma_f32 v139, v103, s36, v142 clamp
	v_fma_f32 v140, v104, s36, v142 clamp
	v_fma_f32 v141, v105, s36, v142 clamp
	v_fma_f32 v134, v106, s36, v142 clamp
	v_fma_f32 v135, v107, s36, v142 clamp
	v_fma_f32 v136, v108, s36, v142 clamp
	v_fma_f32 v137, v109, s36, v142 clamp
	v_add_f32_e32 v138, v138, v134
	v_add_f32_e32 v139, v139, v135
	v_add_f32_e32 v140, v140, v136
	v_add_f32_e32 v141, v141, v137
	v_fma_f32 v134, v110, s36, v142 clamp
	v_fma_f32 v135, v111, s36, v142 clamp
	v_fma_f32 v136, v112, s36, v142 clamp
	v_fma_f32 v137, v113, s36, v142 clamp
	v_add_f32_e32 v138, v138, v134
	v_add_f32_e32 v139, v139, v135
	v_add_f32_e32 v140, v140, v136
	v_add_f32_e32 v141, v141, v137
	v_fma_f32 v134, v114, s36, v142 clamp
	v_fma_f32 v135, v115, s36, v142 clamp
	v_fma_f32 v136, v116, s36, v142 clamp
	v_fma_f32 v137, v117, s36, v142 clamp
	v_add_f32_e32 v138, v138, v134
	v_add_f32_e32 v139, v139, v135
	v_add_f32_e32 v140, v140, v136
	v_add_f32_e32 v141, v141, v137
	v_fma_f32 v134, v118, s36, v142 clamp
	v_fma_f32 v135, v119, s36, v142 clamp
	v_fma_f32 v136, v120, s36, v142 clamp
	v_fma_f32 v137, v121, s36, v142 clamp
	v_add_f32_e32 v138, v138, v134
	v_add_f32_e32 v139, v139, v135
	v_add_f32_e32 v140, v140, v136
	v_add_f32_e32 v141, v141, v137
	v_fma_f32 v134, v122, s36, v142 clamp
	v_fma_f32 v135, v123, s36, v142 clamp
	v_fma_f32 v136, v124, s36, v142 clamp
	v_fma_f32 v137, v125, s36, v142 clamp
	v_add_f32_e32 v138, v138, v134
	v_add_f32_e32 v139, v139, v135
	v_add_f32_e32 v140, v140, v136
	v_add_f32_e32 v141, v141, v137
	v_fma_f32 v134, v126, s36, v142 clamp
	v_fma_f32 v135, v127, s36, v142 clamp
	v_fma_f32 v136, v128, s36, v142 clamp
	v_fma_f32 v137, v129, s36, v142 clamp
	v_add_f32_e32 v138, v138, v134
	v_add_f32_e32 v139, v139, v135
	v_add_f32_e32 v140, v140, v136
	v_add_f32_e32 v141, v141, v137
	v_fma_f32 v134, v130, s36, v142 clamp
	v_fma_f32 v135, v131, s36, v142 clamp
	v_fma_f32 v136, v132, s36, v142 clamp
	v_fma_f32 v137, v133, s36, v142 clamp
	v_add_f32_e32 v138, v138, v134
	v_add_f32_e32 v139, v139, v135
	v_add_f32_e32 v140, v140, v136
	v_add_f32_e32 v141, v141, v137
	v_add_f32_e32 v138, v138, v140
	v_add_f32_e32 v139, v139, v141
	v_add_f32_e32 v138, v138, v139
	v_cvt_u32_f32_e32 v138, v138
	s_nop 1
	v_add_u32_dpp v138, v138, v138 quad_perm:[1,0,3,2] row_mask:0xf bank_mask:0xf bound_ctrl:1
	s_nop 1
	v_add_u32_dpp v138, v138, v138 quad_perm:[2,3,0,1] row_mask:0xf bank_mask:0xf bound_ctrl:1
	s_nop 1
	v_add_u32_dpp v138, v138, v138 row_half_mirror row_mask:0xf bank_mask:0xf bound_ctrl:1
	s_nop 1
	v_add_u32_dpp v138, v138, v138 row_mirror row_mask:0xf bank_mask:0xf bound_ctrl:1
	s_nop 1
	v_readlane_b32 s0, v138, 0
	v_readlane_b32 s1, v138, 16
	s_add_i32 s0, s0, s1
	v_readlane_b32 s1, v138, 32
	s_add_i32 s0, s0, s1
	v_readlane_b32 s1, v138, 48
	s_add_i32 s0, s0, s1
	s_sub_i32 s0, 0x800, s0
	s_cmpk_lt_u32 s0, 0x100
	s_cbranch_scc1 .Lsel_bis_hi
	s_mov_b32 s29, s6
	s_mov_b32 s31, s0
	s_cmpk_eq_u32 s0, 0x100
	s_cbranch_scc0 .Lsel_bis
	s_branch .Lsel_bis_done
.Lsel_bis_hi:
	s_mov_b32 s30, s6
	s_branch .Lsel_bis
.Lsel_bis_done:
	s_mov_b32 s7, s29
	s_sub_u32 s1, s7, 0x60800000
	s_cmp_lt_u32 s1, 0x3f000000
	s_cbranch_scc0 .Lsel_nosnap2
	s_mov_b32 s1, 0x9f800000
	s_cmp_lt_u32 s7, 0x80000000
	s_cselect_b32 s1, 0x80000000, s1
	s_cmp_eq_u32 s7, 0x80000000
	s_cselect_b32 s7, s7, s1
.Lsel_nosnap2:
	s_xor_b32 s1, s7, 0x80000000
	s_not_b32 s0, s7
	s_bitcmp1_b32 s7, 31
	s_cselect_b32 s0, s1, s0
	s_cmpk_eq_u32 s31, 0x100
	s_cbranch_scc0 .Lsel_ties
.Lsel_mask:
	v_mov_b32_e32 v142, s0
	v_mul_f32_e32 v142, s37, v142
	v_mov_b32_e32 v147, 0
	v_mov_b32_e32 v148, 0
	v_fma_f32 v134, v102, s36, v142 clamp
	v_fmamk_f32 v147, v134, 0x3f800000, v147
	v_fma_f32 v135, v103, s36, v142 clamp
	v_fmamk_f32 v147, v135, 0x40000000, v147
	v_fma_f32 v136, v104, s36, v142 clamp
	v_fmamk_f32 v147, v136, 0x40800000, v147
	v_fma_f32 v137, v105, s36, v142 clamp
	v_fmamk_f32 v147, v137, 0x41000000, v147
	v_fma_f32 v134, v106, s36, v142 clamp
	v_fmamk_f32 v147, v134, 0x41800000, v147
	v_fma_f32 v135, v107, s36, v142 clamp
	v_fmamk_f32 v147, v135, 0x42000000, v147
	v_fma_f32 v136, v108, s36, v142 clamp
	v_fmamk_f32 v147, v136, 0x42800000, v147
	v_fma_f32 v137, v109, s36, v142 clamp
	v_fmamk_f32 v147, v137, 0x43000000, v147
	v_fma_f32 v134, v110, s36, v142 clamp
	v_fmamk_f32 v147, v134, 0x43800000, v147
	v_fma_f32 v135, v111, s36, v142 clamp
	v_fmamk_f32 v147, v135, 0x44000000, v147
	v_fma_f32 v136, v112, s36, v142 clamp
	v_fmamk_f32 v147, v136, 0x44800000, v147
	v_fma_f32 v137, v113, s36, v142 clamp
	v_fmamk_f32 v147, v137, 0x45000000, v147
	v_fma_f32 v134, v114, s36, v142 clamp
	v_fmamk_f32 v147, v134, 0x45800000, v147
	v_fma_f32 v135, v115, s36, v142 clamp
	v_fmamk_f32 v147, v135, 0x46000000, v147
	v_fma_f32 v136, v116, s36, v142 clamp
	v_fmamk_f32 v147, v136, 0x46800000, v147
	v_fma_f32 v137, v117, s36, v142 clamp
	v_fmamk_f32 v147, v137, 0x47000000, v147
	v_fma_f32 v134, v118, s36, v142 clamp
	v_fmamk_f32 v148, v134, 0x3f800000, v148
	v_fma_f32 v135, v119, s36, v142 clamp
	v_fmamk_f32 v148, v135, 0x40000000, v148
	v_fma_f32 v136, v120, s36, v142 clamp
	v_fmamk_f32 v148, v136, 0x40800000, v148
	v_fma_f32 v137, v121, s36, v142 clamp
	v_fmamk_f32 v148, v137, 0x41000000, v148
	v_fma_f32 v134, v122, s36, v142 clamp
	v_fmamk_f32 v148, v134, 0x41800000, v148
	v_fma_f32 v135, v123, s36, v142 clamp
	v_fmamk_f32 v148, v135, 0x42000000, v148
	v_fma_f32 v136, v124, s36, v142 clamp
	v_fmamk_f32 v148, v136, 0x42800000, v148
	v_fma_f32 v137, v125, s36, v142 clamp
	v_fmamk_f32 v148, v137, 0x43000000, v148
	v_fma_f32 v134, v126, s36, v142 clamp
	v_fmamk_f32 v148, v134, 0x43800000, v148
	v_fma_f32 v135, v127, s36, v142 clamp
	v_fmamk_f32 v148, v135, 0x44000000, v148
	v_fma_f32 v136, v128, s36, v142 clamp
	v_fmamk_f32 v148, v136, 0x44800000, v148
	v_fma_f32 v137, v129, s36, v142 clamp
	v_fmamk_f32 v148, v137, 0x45000000, v148
	v_fma_f32 v134, v130, s36, v142 clamp
	v_fmamk_f32 v148, v134, 0x45800000, v148
	v_fma_f32 v135, v131, s36, v142 clamp
	v_fmamk_f32 v148, v135, 0x46000000, v148
	v_fma_f32 v136, v132, s36, v142 clamp
	v_fmamk_f32 v148, v136, 0x46800000, v148
	v_fma_f32 v137, v133, s36, v142 clamp
	v_fmamk_f32 v148, v137, 0x47000000, v148
	v_cvt_u32_f32_e32 v147, v147
	v_cvt_u32_f32_e32 v148, v148
	v_lshl_or_b32 v146, v148, 16, v147
	v_not_b32_e32 v146, v146
.Lsel_store:
	s_add_i32 s0, s27, s28
	s_lshl_b32 s0, s0, 8
	s_add_u32 s0, s0, 0x13000000
	s_add_u32 s42, s40, s0
	s_addc_u32 s43, s41, 0
	global_store_dword v152, v146, s[42:43]
	s_add_i32 s4, s4, 1
	s_cmp_lt_u32 s4, 2
	s_cbranch_scc1 .Lsel_row
	s_branch .LBB0_808
.Lsel_ties:
	v_mov_b32_e32 v150, s0
	v_mul_f32_e32 v142, s37, v150
	v_fma_f32 v138, v102, s37, -v142 clamp
	v_fma_f32 v139, v103, s37, -v142 clamp
	v_fma_f32 v140, v104, s37, -v142 clamp
	v_fma_f32 v141, v105, s37, -v142 clamp
	v_fma_f32 v134, v106, s37, -v142 clamp
	v_fma_f32 v135, v107, s37, -v142 clamp
	v_fma_f32 v136, v108, s37, -v142 clamp
	v_fma_f32 v137, v109, s37, -v142 clamp
	v_pk_add_f32 v[138:139], v[138:139], v[134:135]
	v_pk_add_f32 v[140:141], v[140:141], v[136:137]
	v_fma_f32 v134, v110, s37, -v142 clamp
	v_fma_f32 v135, v111, s37, -v142 clamp
	v_fma_f32 v136, v112, s37, -v142 clamp
	v_fma_f32 v137, v113, s37, -v142 clamp
	v_pk_add_f32 v[138:139], v[138:139], v[134:135]
	v_pk_add_f32 v[140:141], v[140:141], v[136:137]
	v_fma_f32 v134, v114, s37, -v142 clamp
	v_fma_f32 v135, v115, s37, -v142 clamp
	v_fma_f32 v136, v116, s37, -v142 clamp
	v_fma_f32 v137, v117, s37, -v142 clamp
	v_pk_add_f32 v[138:139], v[138:139], v[134:135]
	v_pk_add_f32 v[140:141], v[140:141], v[136:137]
	v_fma_f32 v134, v118, s37, -v142 clamp
	v_fma_f32 v135, v119, s37, -v142 clamp
	v_fma_f32 v136, v120, s37, -v142 clamp
	v_fma_f32 v137, v121, s37, -v142 clamp
	v_pk_add_f32 v[138:139], v[138:139], v[134:135]
	v_pk_add_f32 v[140:141], v[140:141], v[136:137]
	v_fma_f32 v134, v122, s37, -v142 clamp
	v_fma_f32 v135, v123, s37, -v142 clamp
	v_fma_f32 v136, v124, s37, -v142 clamp
	v_fma_f32 v137, v125, s37, -v142 clamp
	v_pk_add_f32 v[138:139], v[138:139], v[134:135]
	v_pk_add_f32 v[140:141], v[140:141], v[136:137]
	v_fma_f32 v134, v126, s37, -v142 clamp
	v_fma_f32 v135, v127, s37, -v142 clamp
	v_fma_f32 v136, v128, s37, -v142 clamp
	v_fma_f32 v137, v129, s37, -v142 clamp
	v_pk_add_f32 v[138:139], v[138:139], v[134:135]
	v_pk_add_f32 v[140:141], v[140:141], v[136:137]
	v_fma_f32 v134, v130, s37, -v142 clamp
	v_fma_f32 v135, v131, s37, -v142 clamp
	v_fma_f32 v136, v132, s37, -v142 clamp
	v_fma_f32 v137, v133, s37, -v142 clamp
	v_pk_add_f32 v[138:139], v[138:139], v[134:135]
	v_pk_add_f32 v[140:141], v[140:141], v[136:137]
	v_pk_add_f32 v[138:139], v[138:139], v[140:141]
	v_add_f32_e32 v138, v138, v139
	v_cvt_u32_f32_e32 v138, v138
	s_nop 1
	v_add_u32_dpp v138, v138, v138 quad_perm:[1,0,3,2] row_mask:0xf bank_mask:0xf bound_ctrl:1
	s_nop 1
	v_add_u32_dpp v138, v138, v138 quad_perm:[2,3,0,1] row_mask:0xf bank_mask:0xf bound_ctrl:1
	s_nop 1
	v_add_u32_dpp v138, v138, v138 row_half_mirror row_mask:0xf bank_mask:0xf bound_ctrl:1
	s_nop 1
	v_add_u32_dpp v138, v138, v138 row_mirror row_mask:0xf bank_mask:0xf bound_ctrl:1
	s_nop 1
	v_readlane_b32 s0, v138, 0
	v_readlane_b32 s1, v138, 16
	s_add_i32 s0, s0, s1
	v_readlane_b32 s1, v138, 32
	s_add_i32 s0, s0, s1
	v_readlane_b32 s1, v138, 48
	s_add_i32 s0, s0, s1
	s_sub_i32 s38, 0x100, s0
	s_mov_b32 s39, 0
	v_mov_b32_e32 v146, 0
	v_cmp_eq_f32_e64 s[42:43], v102, v150
	v_fma_f32 v134, v102, s37, -v142 clamp
	v_cvt_u32_f32_e32 v134, v134
	v_mbcnt_lo_u32_b32 v135, s42, 0
	v_mbcnt_hi_u32_b32 v135, s43, v135
	v_add_u32_e32 v135, s39, v135
	v_cmp_gt_u32_e32 vcc, s38, v135
	s_nop 1
	s_and_b64 vcc, vcc, s[42:43]
	s_nop 1
	v_cndmask_b32_e64 v136, 0, 1, vcc
	v_or_b32_e32 v136, v136, v134
	v_lshl_or_b32 v146, v136, 0, v146
	s_bcnt1_i32_b64 s0, s[42:43]
	s_add_i32 s39, s39, s0
	v_cmp_eq_f32_e64 s[42:43], v103, v150
	v_fma_f32 v134, v103, s37, -v142 clamp
	v_cvt_u32_f32_e32 v134, v134
	v_mbcnt_lo_u32_b32 v135, s42, 0
	v_mbcnt_hi_u32_b32 v135, s43, v135
	v_add_u32_e32 v135, s39, v135
	v_cmp_gt_u32_e32 vcc, s38, v135
	s_nop 1
	s_and_b64 vcc, vcc, s[42:43]
	s_nop 1
	v_cndmask_b32_e64 v136, 0, 1, vcc
	v_or_b32_e32 v136, v136, v134
	v_lshl_or_b32 v146, v136, 1, v146
	s_bcnt1_i32_b64 s0, s[42:43]
	s_add_i32 s39, s39, s0
	v_cmp_eq_f32_e64 s[42:43], v104, v150
	v_fma_f32 v134, v104, s37, -v142 clamp
	v_cvt_u32_f32_e32 v134, v134
	v_mbcnt_lo_u32_b32 v135, s42, 0
	v_mbcnt_hi_u32_b32 v135, s43, v135
	v_add_u32_e32 v135, s39, v135
	v_cmp_gt_u32_e32 vcc, s38, v135
	s_nop 1
	s_and_b64 vcc, vcc, s[42:43]
	s_nop 1
	v_cndmask_b32_e64 v136, 0, 1, vcc
	v_or_b32_e32 v136, v136, v134
	v_lshl_or_b32 v146, v136, 2, v146
	s_bcnt1_i32_b64 s0, s[42:43]
	s_add_i32 s39, s39, s0
	v_cmp_eq_f32_e64 s[42:43], v105, v150
	v_fma_f32 v134, v105, s37, -v142 clamp
	v_cvt_u32_f32_e32 v134, v134
	v_mbcnt_lo_u32_b32 v135, s42, 0
	v_mbcnt_hi_u32_b32 v135, s43, v135
	v_add_u32_e32 v135, s39, v135
	v_cmp_gt_u32_e32 vcc, s38, v135
	s_nop 1
	s_and_b64 vcc, vcc, s[42:43]
	s_nop 1
	v_cndmask_b32_e64 v136, 0, 1, vcc
	v_or_b32_e32 v136, v136, v134
	v_lshl_or_b32 v146, v136, 3, v146
	s_bcnt1_i32_b64 s0, s[42:43]
	s_add_i32 s39, s39, s0
	v_cmp_eq_f32_e64 s[42:43], v106, v150
	v_fma_f32 v134, v106, s37, -v142 clamp
	v_cvt_u32_f32_e32 v134, v134
	v_mbcnt_lo_u32_b32 v135, s42, 0
	v_mbcnt_hi_u32_b32 v135, s43, v135
	v_add_u32_e32 v135, s39, v135
	v_cmp_gt_u32_e32 vcc, s38, v135
	s_nop 1
	s_and_b64 vcc, vcc, s[42:43]
	s_nop 1
	v_cndmask_b32_e64 v136, 0, 1, vcc
	v_or_b32_e32 v136, v136, v134
	v_lshl_or_b32 v146, v136, 4, v146
	s_bcnt1_i32_b64 s0, s[42:43]
	s_add_i32 s39, s39, s0
	v_cmp_eq_f32_e64 s[42:43], v107, v150
	v_fma_f32 v134, v107, s37, -v142 clamp
	v_cvt_u32_f32_e32 v134, v134
	v_mbcnt_lo_u32_b32 v135, s42, 0
	v_mbcnt_hi_u32_b32 v135, s43, v135
	v_add_u32_e32 v135, s39, v135
	v_cmp_gt_u32_e32 vcc, s38, v135
	s_nop 1
	s_and_b64 vcc, vcc, s[42:43]
	s_nop 1
	v_cndmask_b32_e64 v136, 0, 1, vcc
	v_or_b32_e32 v136, v136, v134
	v_lshl_or_b32 v146, v136, 5, v146
	s_bcnt1_i32_b64 s0, s[42:43]
	s_add_i32 s39, s39, s0
	v_cmp_eq_f32_e64 s[42:43], v108, v150
	v_fma_f32 v134, v108, s37, -v142 clamp
	v_cvt_u32_f32_e32 v134, v134
	v_mbcnt_lo_u32_b32 v135, s42, 0
	v_mbcnt_hi_u32_b32 v135, s43, v135
	v_add_u32_e32 v135, s39, v135
	v_cmp_gt_u32_e32 vcc, s38, v135
	s_nop 1
	s_and_b64 vcc, vcc, s[42:43]
	s_nop 1
	v_cndmask_b32_e64 v136, 0, 1, vcc
	v_or_b32_e32 v136, v136, v134
	v_lshl_or_b32 v146, v136, 6, v146
	s_bcnt1_i32_b64 s0, s[42:43]
	s_add_i32 s39, s39, s0
	v_cmp_eq_f32_e64 s[42:43], v109, v150
	v_fma_f32 v134, v109, s37, -v142 clamp
	v_cvt_u32_f32_e32 v134, v134
	v_mbcnt_lo_u32_b32 v135, s42, 0
	v_mbcnt_hi_u32_b32 v135, s43, v135
	v_add_u32_e32 v135, s39, v135
	v_cmp_gt_u32_e32 vcc, s38, v135
	s_nop 1
	s_and_b64 vcc, vcc, s[42:43]
	s_nop 1
	v_cndmask_b32_e64 v136, 0, 1, vcc
	v_or_b32_e32 v136, v136, v134
	v_lshl_or_b32 v146, v136, 7, v146
	s_bcnt1_i32_b64 s0, s[42:43]
	s_add_i32 s39, s39, s0
	v_cmp_eq_f32_e64 s[42:43], v110, v150
	v_fma_f32 v134, v110, s37, -v142 clamp
	v_cvt_u32_f32_e32 v134, v134
	v_mbcnt_lo_u32_b32 v135, s42, 0
	v_mbcnt_hi_u32_b32 v135, s43, v135
	v_add_u32_e32 v135, s39, v135
	v_cmp_gt_u32_e32 vcc, s38, v135
	s_nop 1
	s_and_b64 vcc, vcc, s[42:43]
	s_nop 1
	v_cndmask_b32_e64 v136, 0, 1, vcc
	v_or_b32_e32 v136, v136, v134
	v_lshl_or_b32 v146, v136, 8, v146
	s_bcnt1_i32_b64 s0, s[42:43]
	s_add_i32 s39, s39, s0
	v_cmp_eq_f32_e64 s[42:43], v111, v150
	v_fma_f32 v134, v111, s37, -v142 clamp
	v_cvt_u32_f32_e32 v134, v134
	v_mbcnt_lo_u32_b32 v135, s42, 0
	v_mbcnt_hi_u32_b32 v135, s43, v135
	v_add_u32_e32 v135, s39, v135
	v_cmp_gt_u32_e32 vcc, s38, v135
	s_nop 1
	s_and_b64 vcc, vcc, s[42:43]
	s_nop 1
	v_cndmask_b32_e64 v136, 0, 1, vcc
	v_or_b32_e32 v136, v136, v134
	v_lshl_or_b32 v146, v136, 9, v146
	s_bcnt1_i32_b64 s0, s[42:43]
	s_add_i32 s39, s39, s0
	v_cmp_eq_f32_e64 s[42:43], v112, v150
	v_fma_f32 v134, v112, s37, -v142 clamp
	v_cvt_u32_f32_e32 v134, v134
	v_mbcnt_lo_u32_b32 v135, s42, 0
	v_mbcnt_hi_u32_b32 v135, s43, v135
	v_add_u32_e32 v135, s39, v135
	v_cmp_gt_u32_e32 vcc, s38, v135
	s_nop 1
	s_and_b64 vcc, vcc, s[42:43]
	s_nop 1
	v_cndmask_b32_e64 v136, 0, 1, vcc
	v_or_b32_e32 v136, v136, v134
	v_lshl_or_b32 v146, v136, 10, v146
	s_bcnt1_i32_b64 s0, s[42:43]
	s_add_i32 s39, s39, s0
	v_cmp_eq_f32_e64 s[42:43], v113, v150
	v_fma_f32 v134, v113, s37, -v142 clamp
	v_cvt_u32_f32_e32 v134, v134
	v_mbcnt_lo_u32_b32 v135, s42, 0
	v_mbcnt_hi_u32_b32 v135, s43, v135
	v_add_u32_e32 v135, s39, v135
	v_cmp_gt_u32_e32 vcc, s38, v135
	s_nop 1
	s_and_b64 vcc, vcc, s[42:43]
	s_nop 1
	v_cndmask_b32_e64 v136, 0, 1, vcc
	v_or_b32_e32 v136, v136, v134
	v_lshl_or_b32 v146, v136, 11, v146
	s_bcnt1_i32_b64 s0, s[42:43]
	s_add_i32 s39, s39, s0
	v_cmp_eq_f32_e64 s[42:43], v114, v150
	v_fma_f32 v134, v114, s37, -v142 clamp
	v_cvt_u32_f32_e32 v134, v134
	v_mbcnt_lo_u32_b32 v135, s42, 0
	v_mbcnt_hi_u32_b32 v135, s43, v135
	v_add_u32_e32 v135, s39, v135
	v_cmp_gt_u32_e32 vcc, s38, v135
	s_nop 1
	s_and_b64 vcc, vcc, s[42:43]
	s_nop 1
	v_cndmask_b32_e64 v136, 0, 1, vcc
	v_or_b32_e32 v136, v136, v134
	v_lshl_or_b32 v146, v136, 12, v146
	s_bcnt1_i32_b64 s0, s[42:43]
	s_add_i32 s39, s39, s0
	v_cmp_eq_f32_e64 s[42:43], v115, v150
	v_fma_f32 v134, v115, s37, -v142 clamp
	v_cvt_u32_f32_e32 v134, v134
	v_mbcnt_lo_u32_b32 v135, s42, 0
	v_mbcnt_hi_u32_b32 v135, s43, v135
	v_add_u32_e32 v135, s39, v135
	v_cmp_gt_u32_e32 vcc, s38, v135
	s_nop 1
	s_and_b64 vcc, vcc, s[42:43]
	s_nop 1
	v_cndmask_b32_e64 v136, 0, 1, vcc
	v_or_b32_e32 v136, v136, v134
	v_lshl_or_b32 v146, v136, 13, v146
	s_bcnt1_i32_b64 s0, s[42:43]
	s_add_i32 s39, s39, s0
	v_cmp_eq_f32_e64 s[42:43], v116, v150
	v_fma_f32 v134, v116, s37, -v142 clamp
	v_cvt_u32_f32_e32 v134, v134
	v_mbcnt_lo_u32_b32 v135, s42, 0
	v_mbcnt_hi_u32_b32 v135, s43, v135
	v_add_u32_e32 v135, s39, v135
	v_cmp_gt_u32_e32 vcc, s38, v135
	s_nop 1
	s_and_b64 vcc, vcc, s[42:43]
	s_nop 1
	v_cndmask_b32_e64 v136, 0, 1, vcc
	v_or_b32_e32 v136, v136, v134
	v_lshl_or_b32 v146, v136, 14, v146
	s_bcnt1_i32_b64 s0, s[42:43]
	s_add_i32 s39, s39, s0
	v_cmp_eq_f32_e64 s[42:43], v117, v150
	v_fma_f32 v134, v117, s37, -v142 clamp
	v_cvt_u32_f32_e32 v134, v134
	v_mbcnt_lo_u32_b32 v135, s42, 0
	v_mbcnt_hi_u32_b32 v135, s43, v135
	v_add_u32_e32 v135, s39, v135
	v_cmp_gt_u32_e32 vcc, s38, v135
	s_nop 1
	s_and_b64 vcc, vcc, s[42:43]
	s_nop 1
	v_cndmask_b32_e64 v136, 0, 1, vcc
	v_or_b32_e32 v136, v136, v134
	v_lshl_or_b32 v146, v136, 15, v146
	s_bcnt1_i32_b64 s0, s[42:43]
	s_add_i32 s39, s39, s0
	v_cmp_eq_f32_e64 s[42:43], v118, v150
	v_fma_f32 v134, v118, s37, -v142 clamp
	v_cvt_u32_f32_e32 v134, v134
	v_mbcnt_lo_u32_b32 v135, s42, 0
	v_mbcnt_hi_u32_b32 v135, s43, v135
	v_add_u32_e32 v135, s39, v135
	v_cmp_gt_u32_e32 vcc, s38, v135
	s_nop 1
	s_and_b64 vcc, vcc, s[42:43]
	s_nop 1
	v_cndmask_b32_e64 v136, 0, 1, vcc
	v_or_b32_e32 v136, v136, v134
	v_lshl_or_b32 v146, v136, 16, v146
	s_bcnt1_i32_b64 s0, s[42:43]
	s_add_i32 s39, s39, s0
	v_cmp_eq_f32_e64 s[42:43], v119, v150
	v_fma_f32 v134, v119, s37, -v142 clamp
	v_cvt_u32_f32_e32 v134, v134
	v_mbcnt_lo_u32_b32 v135, s42, 0
	v_mbcnt_hi_u32_b32 v135, s43, v135
	v_add_u32_e32 v135, s39, v135
	v_cmp_gt_u32_e32 vcc, s38, v135
	s_nop 1
	s_and_b64 vcc, vcc, s[42:43]
	s_nop 1
	v_cndmask_b32_e64 v136, 0, 1, vcc
	v_or_b32_e32 v136, v136, v134
	v_lshl_or_b32 v146, v136, 17, v146
	s_bcnt1_i32_b64 s0, s[42:43]
	s_add_i32 s39, s39, s0
	v_cmp_eq_f32_e64 s[42:43], v120, v150
	v_fma_f32 v134, v120, s37, -v142 clamp
	v_cvt_u32_f32_e32 v134, v134
	v_mbcnt_lo_u32_b32 v135, s42, 0
	v_mbcnt_hi_u32_b32 v135, s43, v135
	v_add_u32_e32 v135, s39, v135
	v_cmp_gt_u32_e32 vcc, s38, v135
	s_nop 1
	s_and_b64 vcc, vcc, s[42:43]
	s_nop 1
	v_cndmask_b32_e64 v136, 0, 1, vcc
	v_or_b32_e32 v136, v136, v134
	v_lshl_or_b32 v146, v136, 18, v146
	s_bcnt1_i32_b64 s0, s[42:43]
	s_add_i32 s39, s39, s0
	v_cmp_eq_f32_e64 s[42:43], v121, v150
	v_fma_f32 v134, v121, s37, -v142 clamp
	v_cvt_u32_f32_e32 v134, v134
	v_mbcnt_lo_u32_b32 v135, s42, 0
	v_mbcnt_hi_u32_b32 v135, s43, v135
	v_add_u32_e32 v135, s39, v135
	v_cmp_gt_u32_e32 vcc, s38, v135
	s_nop 1
	s_and_b64 vcc, vcc, s[42:43]
	s_nop 1
	v_cndmask_b32_e64 v136, 0, 1, vcc
	v_or_b32_e32 v136, v136, v134
	v_lshl_or_b32 v146, v136, 19, v146
	s_bcnt1_i32_b64 s0, s[42:43]
	s_add_i32 s39, s39, s0
	v_cmp_eq_f32_e64 s[42:43], v122, v150
	v_fma_f32 v134, v122, s37, -v142 clamp
	v_cvt_u32_f32_e32 v134, v134
	v_mbcnt_lo_u32_b32 v135, s42, 0
	v_mbcnt_hi_u32_b32 v135, s43, v135
	v_add_u32_e32 v135, s39, v135
	v_cmp_gt_u32_e32 vcc, s38, v135
	s_nop 1
	s_and_b64 vcc, vcc, s[42:43]
	s_nop 1
	v_cndmask_b32_e64 v136, 0, 1, vcc
	v_or_b32_e32 v136, v136, v134
	v_lshl_or_b32 v146, v136, 20, v146
	s_bcnt1_i32_b64 s0, s[42:43]
	s_add_i32 s39, s39, s0
	v_cmp_eq_f32_e64 s[42:43], v123, v150
	v_fma_f32 v134, v123, s37, -v142 clamp
	v_cvt_u32_f32_e32 v134, v134
	v_mbcnt_lo_u32_b32 v135, s42, 0
	v_mbcnt_hi_u32_b32 v135, s43, v135
	v_add_u32_e32 v135, s39, v135
	v_cmp_gt_u32_e32 vcc, s38, v135
	s_nop 1
	s_and_b64 vcc, vcc, s[42:43]
	s_nop 1
	v_cndmask_b32_e64 v136, 0, 1, vcc
	v_or_b32_e32 v136, v136, v134
	v_lshl_or_b32 v146, v136, 21, v146
	s_bcnt1_i32_b64 s0, s[42:43]
	s_add_i32 s39, s39, s0
	v_cmp_eq_f32_e64 s[42:43], v124, v150
	v_fma_f32 v134, v124, s37, -v142 clamp
	v_cvt_u32_f32_e32 v134, v134
	v_mbcnt_lo_u32_b32 v135, s42, 0
	v_mbcnt_hi_u32_b32 v135, s43, v135
	v_add_u32_e32 v135, s39, v135
	v_cmp_gt_u32_e32 vcc, s38, v135
	s_nop 1
	s_and_b64 vcc, vcc, s[42:43]
	s_nop 1
	v_cndmask_b32_e64 v136, 0, 1, vcc
	v_or_b32_e32 v136, v136, v134
	v_lshl_or_b32 v146, v136, 22, v146
	s_bcnt1_i32_b64 s0, s[42:43]
	s_add_i32 s39, s39, s0
	v_cmp_eq_f32_e64 s[42:43], v125, v150
	v_fma_f32 v134, v125, s37, -v142 clamp
	v_cvt_u32_f32_e32 v134, v134
	v_mbcnt_lo_u32_b32 v135, s42, 0
	v_mbcnt_hi_u32_b32 v135, s43, v135
	v_add_u32_e32 v135, s39, v135
	v_cmp_gt_u32_e32 vcc, s38, v135
	s_nop 1
	s_and_b64 vcc, vcc, s[42:43]
	s_nop 1
	v_cndmask_b32_e64 v136, 0, 1, vcc
	v_or_b32_e32 v136, v136, v134
	v_lshl_or_b32 v146, v136, 23, v146
	s_bcnt1_i32_b64 s0, s[42:43]
	s_add_i32 s39, s39, s0
	v_cmp_eq_f32_e64 s[42:43], v126, v150
	v_fma_f32 v134, v126, s37, -v142 clamp
	v_cvt_u32_f32_e32 v134, v134
	v_mbcnt_lo_u32_b32 v135, s42, 0
	v_mbcnt_hi_u32_b32 v135, s43, v135
	v_add_u32_e32 v135, s39, v135
	v_cmp_gt_u32_e32 vcc, s38, v135
	s_nop 1
	s_and_b64 vcc, vcc, s[42:43]
	s_nop 1
	v_cndmask_b32_e64 v136, 0, 1, vcc
	v_or_b32_e32 v136, v136, v134
	v_lshl_or_b32 v146, v136, 24, v146
	s_bcnt1_i32_b64 s0, s[42:43]
	s_add_i32 s39, s39, s0
	v_cmp_eq_f32_e64 s[42:43], v127, v150
	v_fma_f32 v134, v127, s37, -v142 clamp
	v_cvt_u32_f32_e32 v134, v134
	v_mbcnt_lo_u32_b32 v135, s42, 0
	v_mbcnt_hi_u32_b32 v135, s43, v135
	v_add_u32_e32 v135, s39, v135
	v_cmp_gt_u32_e32 vcc, s38, v135
	s_nop 1
	s_and_b64 vcc, vcc, s[42:43]
	s_nop 1
	v_cndmask_b32_e64 v136, 0, 1, vcc
	v_or_b32_e32 v136, v136, v134
	v_lshl_or_b32 v146, v136, 25, v146
	s_bcnt1_i32_b64 s0, s[42:43]
	s_add_i32 s39, s39, s0
	v_cmp_eq_f32_e64 s[42:43], v128, v150
	v_fma_f32 v134, v128, s37, -v142 clamp
	v_cvt_u32_f32_e32 v134, v134
	v_mbcnt_lo_u32_b32 v135, s42, 0
	v_mbcnt_hi_u32_b32 v135, s43, v135
	v_add_u32_e32 v135, s39, v135
	v_cmp_gt_u32_e32 vcc, s38, v135
	s_nop 1
	s_and_b64 vcc, vcc, s[42:43]
	s_nop 1
	v_cndmask_b32_e64 v136, 0, 1, vcc
	v_or_b32_e32 v136, v136, v134
	v_lshl_or_b32 v146, v136, 26, v146
	s_bcnt1_i32_b64 s0, s[42:43]
	s_add_i32 s39, s39, s0
	v_cmp_eq_f32_e64 s[42:43], v129, v150
	v_fma_f32 v134, v129, s37, -v142 clamp
	v_cvt_u32_f32_e32 v134, v134
	v_mbcnt_lo_u32_b32 v135, s42, 0
	v_mbcnt_hi_u32_b32 v135, s43, v135
	v_add_u32_e32 v135, s39, v135
	v_cmp_gt_u32_e32 vcc, s38, v135
	s_nop 1
	s_and_b64 vcc, vcc, s[42:43]
	s_nop 1
	v_cndmask_b32_e64 v136, 0, 1, vcc
	v_or_b32_e32 v136, v136, v134
	v_lshl_or_b32 v146, v136, 27, v146
	s_bcnt1_i32_b64 s0, s[42:43]
	s_add_i32 s39, s39, s0
	v_cmp_eq_f32_e64 s[42:43], v130, v150
	v_fma_f32 v134, v130, s37, -v142 clamp
	v_cvt_u32_f32_e32 v134, v134
	v_mbcnt_lo_u32_b32 v135, s42, 0
	v_mbcnt_hi_u32_b32 v135, s43, v135
	v_add_u32_e32 v135, s39, v135
	v_cmp_gt_u32_e32 vcc, s38, v135
	s_nop 1
	s_and_b64 vcc, vcc, s[42:43]
	s_nop 1
	v_cndmask_b32_e64 v136, 0, 1, vcc
	v_or_b32_e32 v136, v136, v134
	v_lshl_or_b32 v146, v136, 28, v146
	s_bcnt1_i32_b64 s0, s[42:43]
	s_add_i32 s39, s39, s0
	v_cmp_eq_f32_e64 s[42:43], v131, v150
	v_fma_f32 v134, v131, s37, -v142 clamp
	v_cvt_u32_f32_e32 v134, v134
	v_mbcnt_lo_u32_b32 v135, s42, 0
	v_mbcnt_hi_u32_b32 v135, s43, v135
	v_add_u32_e32 v135, s39, v135
	v_cmp_gt_u32_e32 vcc, s38, v135
	s_nop 1
	s_and_b64 vcc, vcc, s[42:43]
	s_nop 1
	v_cndmask_b32_e64 v136, 0, 1, vcc
	v_or_b32_e32 v136, v136, v134
	v_lshl_or_b32 v146, v136, 29, v146
	s_bcnt1_i32_b64 s0, s[42:43]
	s_add_i32 s39, s39, s0
	v_cmp_eq_f32_e64 s[42:43], v132, v150
	v_fma_f32 v134, v132, s37, -v142 clamp
	v_cvt_u32_f32_e32 v134, v134
	v_mbcnt_lo_u32_b32 v135, s42, 0
	v_mbcnt_hi_u32_b32 v135, s43, v135
	v_add_u32_e32 v135, s39, v135
	v_cmp_gt_u32_e32 vcc, s38, v135
	s_nop 1
	s_and_b64 vcc, vcc, s[42:43]
	s_nop 1
	v_cndmask_b32_e64 v136, 0, 1, vcc
	v_or_b32_e32 v136, v136, v134
	v_lshl_or_b32 v146, v136, 30, v146
	s_bcnt1_i32_b64 s0, s[42:43]
	s_add_i32 s39, s39, s0
	v_cmp_eq_f32_e64 s[42:43], v133, v150
	v_fma_f32 v134, v133, s37, -v142 clamp
	v_cvt_u32_f32_e32 v134, v134
	v_mbcnt_lo_u32_b32 v135, s42, 0
	v_mbcnt_hi_u32_b32 v135, s43, v135
	v_add_u32_e32 v135, s39, v135
	v_cmp_gt_u32_e32 vcc, s38, v135
	s_nop 1
	s_and_b64 vcc, vcc, s[42:43]
	s_nop 1
	v_cndmask_b32_e64 v136, 0, 1, vcc
	v_or_b32_e32 v136, v136, v134
	v_lshl_or_b32 v146, v136, 31, v146
	s_bcnt1_i32_b64 s0, s[42:43]
	s_add_i32 s39, s39, s0
	s_branch .Lsel_store
